# class barriers: the L1 invalidate is issued and awaited by wave 1 while wave 0 runs the arrival/release protocol (release no longer waits for the 1.7 us invalidate)
# speedup vs baseline: 1.0051x; 1.0051x over previous
.LBB0_634:
	s_or_b64 exec, exec, s[14:15]
	s_mov_b32 s53, 0x7ffff
	s_waitcnt vmcnt(0)
	s_barrier
	v_readlane_b32 s0, v211, 0
	s_cmp_eq_u32 s0, 64
	s_cbranch_scc0 .Llb686_w1
	buffer_inv sc1
	s_waitcnt vmcnt(0)
.Llb686_w1:
	s_mov_b64 s[6:7], exec
	v_readlane_b32 s0, v254, 8
	v_readlane_b32 s1, v254, 9
	s_and_b64 s[0:1], s[6:7], s[0:1]
	s_mov_b64 exec, s[0:1]
	s_cbranch_execz .LBB0_686
	v_readlane_b32 s0, v255, 41
	s_cmp_eq_u32 s0, 1
	s_cbranch_scc1 .Llb686_go
	s_cmp_eq_u32 s0, 2
	s_cbranch_scc1 .Llb686_global
	s_add_u32 s2, s92, 0x5000
	s_addc_u32 s3, s93, 0
	s_waitcnt vmcnt(0) lgkmcnt(0)
	global_load_dword v0, v197, s[2:3] offset:128 sc1
	s_waitcnt vmcnt(0)
	v_readfirstlane_b32 s0, v0
	s_cmp_eq_u32 s0, 0
	s_cselect_b32 s0, 1, 2
	s_nop 0
	v_writelane_b32 v255, s0, 41
	s_cmp_eq_u32 s0, 1
	s_cbranch_scc0 .Llb686_global
.Llb686_go:
	s_and_b32 s0, s74, 7
	s_lshl_b32 s0, s0, 8
	s_add_u32 s0, s0, 0x4000
	s_add_u32 s2, s92, s0
	s_addc_u32 s3, s93, 0
	v_mov_b32_e32 v0, 1
	s_waitcnt vmcnt(0) lgkmcnt(0)
	s_add_u32 s12, s92, 0x5100
	s_addc_u32 s13, s93, 0
	global_atomic_add v197, v0, s[12:13]
	global_atomic_add v1, v197, v0, s[2:3] sc0
	s_waitcnt vmcnt(0)
	v_readfirstlane_b32 s1, v1
	s_lshr_b32 s8, s1, 5
	s_and_b32 s1, s1, 31
	s_cmp_eq_u32 s1, 31
	s_cbranch_scc1 .Llb686_lead
	s_mov_b32 s9, 0

.LBB0_738:
	s_waitcnt vmcnt(0)
	s_barrier
	v_readlane_b32 s0, v211, 0
	s_cmp_eq_u32 s0, 64
	s_cbranch_scc0 .Llb790_w1
	buffer_inv sc1
	s_waitcnt vmcnt(0)

.Llb790_go:
	s_and_b32 s0, s74, 7
	s_lshl_b32 s0, s0, 8
	s_add_u32 s0, s0, 0x4000
	s_add_u32 s2, s92, s0
	s_addc_u32 s3, s93, 0
	v_mov_b32_e32 v0, 1
	s_waitcnt vmcnt(0) lgkmcnt(0)
	s_add_u32 s12, s92, 0x5100
	s_addc_u32 s13, s93, 0
	global_load_dword v2, v197, s[12:13] sc1
	global_atomic_add v1, v197, v0, s[2:3] sc0
	s_waitcnt vmcnt(0)
	v_readfirstlane_b32 s1, v1
	s_lshr_b32 s8, s1, 5
	s_and_b32 s1, s1, 31
	s_cmp_eq_u32 s1, 31
	s_cbranch_scc1 .Llb790_lead
	s_mov_b32 s9, 0

.LBB0_830:
	s_waitcnt vmcnt(0)
	s_waitcnt vmcnt(0)
	s_barrier
	v_readlane_b32 s0, v211, 0
	s_cmp_eq_u32 s0, 64
	s_cbranch_scc0 .Llb882_w1
	buffer_inv sc1
	s_waitcnt vmcnt(0)

.Llb882_go:
	s_and_b32 s0, s74, 7
	s_lshl_b32 s0, s0, 8
	s_add_u32 s0, s0, 0x4000
	s_add_u32 s2, s92, s0
	s_addc_u32 s3, s93, 0
	v_mov_b32_e32 v0, 1
	s_waitcnt vmcnt(0) lgkmcnt(0)
	global_atomic_add v1, v197, v0, s[2:3] sc0
	s_waitcnt vmcnt(0)
	v_readfirstlane_b32 s1, v1
	s_lshr_b32 s8, s1, 5
	s_and_b32 s1, s1, 31
	s_cmp_eq_u32 s1, 31
	s_cbranch_scc1 .Llb882_lead
	s_mov_b32 s9, 0
